# DeltaNet prep S5: MFMA operands swapped so each lane holds 4 consecutive output columns - 8 dwordx2 stores per thread instead of 32 two-byte stores, fragment reads batched, half the conversions
# baseline (speedup 1.0000x reference)
.Lsv_b14:
	v_fmac_f32_e32 v108, v212, v106
	v_fmac_f32_e32 v109, v220, v106
	v_fmac_f32_e32 v110, v228, v106
	v_fmac_f32_e32 v111, v236, v106
	s_waitcnt lgkmcnt(0)
	ds_read_b128 v[176:179], v128 offset:15360
	ds_read_b128 v[180:183], v128 offset:15376
	ds_read_b128 v[184:187], v128 offset:15616
	ds_read_b128 v[188:191], v128 offset:15632
	ds_read_b128 v[192:195], v128 offset:15872
	ds_read_b128 v[196:199], v128 offset:15888
	ds_read_b128 v[200:203], v128 offset:16128
	ds_read_b128 v[238:241], v128 offset:16144
	ds_read_b32 v146, v129 offset:15772
	ds_read_b32 v147, v129 offset:16028
	ds_read_b32 v148, v129 offset:16060
	ds_read_b32 v149, v129 offset:16284
	ds_read_b32 v150, v129 offset:16316
	ds_read_b32 v151, v129 offset:16348
	v_add_f32_dpp v108, v108, v108 quad_perm:[1,0,3,2] row_mask:0xf bank_mask:0xf bound_ctrl:1
	v_add_f32_dpp v109, v109, v109 quad_perm:[1,0,3,2] row_mask:0xf bank_mask:0xf bound_ctrl:1
	v_cmp_eq_u32_e32 vcc, 60, v0
	v_add_f32_dpp v110, v110, v110 quad_perm:[1,0,3,2] row_mask:0xf bank_mask:0xf bound_ctrl:1
	v_add_f32_dpp v111, v111, v111 quad_perm:[1,0,3,2] row_mask:0xf bank_mask:0xf bound_ctrl:1
	v_cndmask_b32_e64 v120, 0, 1.0, vcc
	v_cmp_eq_u32_e32 vcc, 61, v0
	v_add_f32_dpp v108, v108, v108 quad_perm:[2,3,0,1] row_mask:0xf bank_mask:0xf bound_ctrl:1
	v_add_f32_dpp v109, v109, v109 quad_perm:[2,3,0,1] row_mask:0xf bank_mask:0xf bound_ctrl:1
	v_cndmask_b32_e64 v121, 0, 1.0, vcc
	v_cmp_eq_u32_e32 vcc, 62, v0
	v_add_f32_dpp v110, v110, v110 quad_perm:[2,3,0,1] row_mask:0xf bank_mask:0xf bound_ctrl:1
	v_add_f32_dpp v111, v111, v111 quad_perm:[2,3,0,1] row_mask:0xf bank_mask:0xf bound_ctrl:1
	v_cndmask_b32_e64 v122, 0, 1.0, vcc
	v_cmp_eq_u32_e32 vcc, 63, v0
	v_add_f32_dpp v108, v108, v108 row_half_mirror row_mask:0xf bank_mask:0xf bound_ctrl:1
	v_add_f32_dpp v109, v109, v109 row_half_mirror row_mask:0xf bank_mask:0xf bound_ctrl:1
	v_cndmask_b32_e64 v123, 0, 1.0, vcc
	v_add_f32_dpp v110, v110, v110 row_half_mirror row_mask:0xf bank_mask:0xf bound_ctrl:1
	v_add_f32_dpp v111, v111, v111 row_half_mirror row_mask:0xf bank_mask:0xf bound_ctrl:1
	v_sub_f32_e32 v124, v116, v108
	v_sub_f32_e32 v125, v117, v109
	v_sub_f32_e32 v126, v118, v110
	v_sub_f32_e32 v127, v119, v111
	v_fma_f32 v125, -v130, v124, v125
	v_fma_f32 v126, -v131, v124, v126
	v_fma_f32 v127, -v133, v124, v127
	s_waitcnt lgkmcnt(13)
	v_mul_f32_e32 v112, v176, v100
	s_waitcnt lgkmcnt(11)
	v_mul_f32_e32 v113, v184, v100
	v_fma_f32 v126, -v132, v125, v126
	v_fma_f32 v127, -v134, v125, v127
	s_waitcnt lgkmcnt(9)
	v_mul_f32_e32 v114, v192, v100
	s_waitcnt lgkmcnt(7)
	v_mul_f32_e32 v115, v200, v100
	v_fma_f32 v127, -v135, v126, v127
	v_fmac_f32_e32 v112, v177, v101
	v_fmac_f32_e32 v113, v185, v101
	v_cndmask_b32_e64 v107, v107, v124, s[6:7]
	v_fmac_f32_e32 v114, v193, v101
	v_cndmask_b32_e64 v107, v107, v125, s[8:9]
	v_fmac_f32_e32 v115, v201, v101
	v_cndmask_b32_e64 v107, v107, v126, s[10:11]
	v_fmac_f32_e32 v112, v178, v102
	v_cndmask_b32_e64 v107, v107, v127, s[12:13]
	v_fmac_f32_e32 v113, v186, v102
	v_fmac_f32_e32 v114, v194, v102
	v_fmac_f32_e32 v115, v202, v102
	v_fmac_f32_e32 v112, v179, v103
	v_fmac_f32_e32 v113, v187, v103
	v_fmac_f32_e32 v114, v195, v103
	v_fmac_f32_e32 v115, v203, v103
	v_fmac_f32_e32 v112, v180, v104
	v_fmac_f32_e32 v113, v188, v104
	v_fmac_f32_e32 v114, v196, v104
	s_waitcnt lgkmcnt(6)
	v_fmac_f32_e32 v115, v238, v104
	v_fmac_f32_e32 v112, v181, v105
	v_fmac_f32_e32 v113, v189, v105
	v_fmac_f32_e32 v114, v197, v105
	v_fmac_f32_e32 v115, v239, v105
	v_fmac_f32_e32 v112, v182, v106
	v_fmac_f32_e32 v113, v190, v106
	v_fmac_f32_e32 v114, v198, v106
	v_fmac_f32_e32 v115, v240, v106
	v_fmac_f32_e32 v112, v183, v107
	v_fmac_f32_e32 v113, v191, v107
	v_fmac_f32_e32 v114, v199, v107
	v_fmac_f32_e32 v115, v241, v107
	v_add_f32_dpp v112, v112, v112 quad_perm:[1,0,3,2] row_mask:0xf bank_mask:0xf bound_ctrl:1
	v_add_f32_dpp v113, v113, v113 quad_perm:[1,0,3,2] row_mask:0xf bank_mask:0xf bound_ctrl:1
	v_add_f32_dpp v114, v114, v114 quad_perm:[1,0,3,2] row_mask:0xf bank_mask:0xf bound_ctrl:1
	v_add_f32_dpp v115, v115, v115 quad_perm:[1,0,3,2] row_mask:0xf bank_mask:0xf bound_ctrl:1
	v_add_f32_dpp v112, v112, v112 quad_perm:[2,3,0,1] row_mask:0xf bank_mask:0xf bound_ctrl:1
	v_add_f32_dpp v113, v113, v113 quad_perm:[2,3,0,1] row_mask:0xf bank_mask:0xf bound_ctrl:1
	v_add_f32_dpp v114, v114, v114 quad_perm:[2,3,0,1] row_mask:0xf bank_mask:0xf bound_ctrl:1
	v_add_f32_dpp v115, v115, v115 quad_perm:[2,3,0,1] row_mask:0xf bank_mask:0xf bound_ctrl:1
	v_add_f32_dpp v112, v112, v112 row_half_mirror row_mask:0xf bank_mask:0xf bound_ctrl:1
	v_add_f32_dpp v113, v113, v113 row_half_mirror row_mask:0xf bank_mask:0xf bound_ctrl:1
	v_add_f32_dpp v114, v114, v114 row_half_mirror row_mask:0xf bank_mask:0xf bound_ctrl:1
	v_add_f32_dpp v115, v115, v115 row_half_mirror row_mask:0xf bank_mask:0xf bound_ctrl:1
	v_sub_f32_e32 v124, v120, v112
	v_sub_f32_e32 v125, v121, v113
	v_sub_f32_e32 v126, v122, v114
	v_sub_f32_e32 v127, v123, v115
	s_waitcnt lgkmcnt(5)
	v_fma_f32 v125, -v146, v124, v125
	s_waitcnt lgkmcnt(4)
	v_fma_f32 v126, -v147, v124, v126
	s_waitcnt lgkmcnt(2)
	v_fma_f32 v127, -v149, v124, v127
	v_fma_f32 v126, -v148, v125, v126
	s_waitcnt lgkmcnt(1)
	v_fma_f32 v127, -v150, v125, v127
	s_waitcnt lgkmcnt(0)
	v_fma_f32 v127, -v151, v126, v127
	v_cndmask_b32_e64 v107, v107, v124, s[14:15]
	v_cndmask_b32_e64 v107, v107, v125, s[16:17]
	v_cndmask_b32_e64 v107, v107, v126, s[18:19]
	v_cndmask_b32_e64 v107, v107, v127, s[20:21]
	v_lshl_add_u32 v152, v0, 2, 0
	v_add_u32_e32 v153, 0x15c00, v152
	v_add_u32_e32 v154, 0x15e00, v152
	v_add_u32_e32 v155, 0x15f00, v152
	ds_read_b32 v153, v153
	ds_read_b32 v154, v154
	ds_read_b32 v155, v155
	v_mul_u32_u24_e32 v156, 0x48, v2
	v_add_lshl_u32 v156, v0, v156, 1
	v_readlane_b32 s6, v244, 27
	v_readlane_b32 s7, v244, 32
	s_lshl_b64 s[8:9], s[36:37], 14
	s_mov_b32 s36, s2
	s_nop 1
	v_add_u32_e32 v157, s6, v156
	v_add_u32_e32 v156, s7, v156
	s_waitcnt lgkmcnt(0)
	v_mul_f32_e32 v154, v153, v154
	v_mul_f32_e32 v154, v154, v155
	v_mul_f32_e32 v158, v100, v153
	v_mul_f32_e32 v159, v100, v154
	v_cvt_pk_bf16_f32 v158, v158, v158
	v_cvt_pk_bf16_f32 v159, v159, v159
	ds_write_b16 v157, v158 offset:0
	ds_write_b16 v156, v159 offset:0
	v_mul_f32_e32 v158, v101, v153
	v_mul_f32_e32 v159, v101, v154
	v_cvt_pk_bf16_f32 v158, v158, v158
	v_cvt_pk_bf16_f32 v159, v159, v159
	ds_write_b16 v157, v158 offset:1152
	ds_write_b16 v156, v159 offset:1152
	v_mul_f32_e32 v158, v102, v153
	v_mul_f32_e32 v159, v102, v154
	v_cvt_pk_bf16_f32 v158, v158, v158
	v_cvt_pk_bf16_f32 v159, v159, v159
	ds_write_b16 v157, v158 offset:2304
	ds_write_b16 v156, v159 offset:2304
	v_mul_f32_e32 v158, v103, v153
	v_mul_f32_e32 v159, v103, v154
	v_cvt_pk_bf16_f32 v158, v158, v158
	v_cvt_pk_bf16_f32 v159, v159, v159
	ds_write_b16 v157, v158 offset:3456
	ds_write_b16 v156, v159 offset:3456
	v_mul_f32_e32 v158, v104, v153
	v_mul_f32_e32 v159, v104, v154
	v_cvt_pk_bf16_f32 v158, v158, v158
	v_cvt_pk_bf16_f32 v159, v159, v159
	ds_write_b16 v157, v158 offset:4608
	ds_write_b16 v156, v159 offset:4608
	v_mul_f32_e32 v158, v105, v153
	v_mul_f32_e32 v159, v105, v154
	v_cvt_pk_bf16_f32 v158, v158, v158
	v_cvt_pk_bf16_f32 v159, v159, v159
	ds_write_b16 v157, v158 offset:5760
	ds_write_b16 v156, v159 offset:5760
	v_mul_f32_e32 v158, v106, v153
	v_mul_f32_e32 v159, v106, v154
	v_cvt_pk_bf16_f32 v158, v158, v158
	v_cvt_pk_bf16_f32 v159, v159, v159
	ds_write_b16 v157, v158 offset:6912
	ds_write_b16 v156, v159 offset:6912
	v_mul_f32_e32 v158, v107, v153
	v_mul_f32_e32 v159, v107, v154
	v_cvt_pk_bf16_f32 v158, v158, v158
	v_cvt_pk_bf16_f32 v159, v159, v159
	ds_write_b16 v157, v158 offset:8064
	ds_write_b16 v156, v159 offset:8064
	v_mul_u32_u24_e32 v0, 0x48, v46
	v_lshlrev_b32_e32 v0, 1, v0
	v_add3_u32 v84, s6, v0, v48
	s_waitcnt lgkmcnt(0)
	s_barrier
	v_lshlrev_b32_e32 v100, 8, v46
	v_lshl_or_b32 v100, v43, 5, v100
	v_lshl_or_b32 v100, v47, 1, v100
	v_lshl_or_b32 v6, v43, 4, v46
	s_movk_i32 s6, 0x90
	v_mul_lo_u32 v6, v6, s6
	v_add3_u32 v56, 0, v6, v48
	v_add3_u32 v0, s7, v0, v48
	s_add_u32 s6, s22, s8
	s_addc_u32 s7, s23, s9
	s_add_u32 s8, s59, s8
	s_addc_u32 s9, s64, s9
	ds_read_b128 v[6:9], v56 offset:35840
	ds_read_b128 v[104:107], v84
	ds_read_b128 v[14:17], v56 offset:35904
	ds_read_b128 v[108:111], v84 offset:64
	ds_read_b128 v[48:51], v56 offset:17408
	ds_read_b128 v[112:115], v0
	ds_read_b128 v[10:13], v56 offset:17472
	ds_read_b128 v[116:119], v0 offset:64
	ds_read_b128 v[120:123], v84 offset:2304
	ds_read_b128 v[124:127], v84 offset:2368
	ds_read_b128 v[128:131], v0 offset:2304
	ds_read_b128 v[132:135], v0 offset:2368
	ds_read_b128 v[176:179], v84 offset:4608
	ds_read_b128 v[180:183], v84 offset:4672
	v_add_u32_e32 v101, 0x1000, v100
	v_add_u32_e32 v102, 0x2000, v100
	v_add_u32_e32 v103, 0x3000, v100
	s_waitcnt lgkmcnt(13)
	s_waitcnt lgkmcnt(12)
	v_mfma_f32_16x16x32_bf16 v[2:5], v[6:9], v[104:107], 0
	ds_read_b128 v[184:187], v0 offset:4608
	ds_read_b128 v[188:191], v0 offset:4672
	s_waitcnt lgkmcnt(11)
	s_waitcnt lgkmcnt(10)
	v_mfma_f32_16x16x32_bf16 v[42:45], v[48:51], v[112:115], 0
	ds_read_b128 v[192:195], v84 offset:6912
	ds_read_b128 v[196:199], v84 offset:6976
	ds_read_b128 v[206:209], v0 offset:6912
	ds_read_b128 v[210:213], v0 offset:6976
	v_mfma_f32_16x16x32_bf16 v[2:5], v[14:17], v[108:111], v[2:5]
	s_waitcnt lgkmcnt(13)
	s_waitcnt lgkmcnt(12)
	v_mfma_f32_16x16x32_bf16 v[42:45], v[10:13], v[116:119], v[42:45]
	s_waitcnt lgkmcnt(11)
	v_mfma_f32_16x16x32_bf16 v[52:55], v[6:9], v[120:123], 0
	s_waitcnt lgkmcnt(9)
	v_mfma_f32_16x16x32_bf16 v[60:63], v[48:51], v[128:131], 0
	v_mfma_f32_16x16x32_bf16 v[52:55], v[14:17], v[124:127], v[52:55]
	s_waitcnt lgkmcnt(8)
	v_mfma_f32_16x16x32_bf16 v[60:63], v[10:13], v[132:135], v[60:63]
	s_waitcnt lgkmcnt(7)
	v_mfma_f32_16x16x32_bf16 v[64:67], v[6:9], v[176:179], 0
	s_waitcnt lgkmcnt(5)
	v_mfma_f32_16x16x32_bf16 v[146:149], v[48:51], v[184:187], 0
	v_mfma_f32_16x16x32_bf16 v[64:67], v[14:17], v[180:183], v[64:67]
	s_waitcnt lgkmcnt(4)
	v_mfma_f32_16x16x32_bf16 v[146:149], v[10:13], v[188:191], v[146:149]
	s_waitcnt lgkmcnt(3)
	v_mfma_f32_16x16x32_bf16 v[150:153], v[6:9], v[192:195], 0
	s_waitcnt lgkmcnt(1)
	v_mfma_f32_16x16x32_bf16 v[154:157], v[48:51], v[206:209], 0
	v_mfma_f32_16x16x32_bf16 v[150:153], v[14:17], v[196:199], v[150:153]
	s_waitcnt lgkmcnt(0)
	v_mfma_f32_16x16x32_bf16 v[154:157], v[10:13], v[210:213], v[154:157]
	s_and_b64 vcc, exec, s[38:39]
	v_cvt_pk_bf16_f32 v2, v2, v3
	v_cvt_pk_bf16_f32 v3, v4, v5
	global_store_dwordx2 v100, v[2:3], s[8:9]
	v_cvt_pk_bf16_f32 v42, v42, v43
	v_cvt_pk_bf16_f32 v43, v44, v45
	global_store_dwordx2 v100, v[42:43], s[6:7]
	v_cvt_pk_bf16_f32 v52, v52, v53
	v_cvt_pk_bf16_f32 v53, v54, v55
	global_store_dwordx2 v101, v[52:53], s[8:9]
	v_cvt_pk_bf16_f32 v60, v60, v61
	v_cvt_pk_bf16_f32 v61, v62, v63
	global_store_dwordx2 v101, v[60:61], s[6:7]
	v_cvt_pk_bf16_f32 v64, v64, v65
	v_cvt_pk_bf16_f32 v65, v66, v67
	global_store_dwordx2 v102, v[64:65], s[8:9]
	v_cvt_pk_bf16_f32 v146, v146, v147
	v_cvt_pk_bf16_f32 v147, v148, v149
	global_store_dwordx2 v102, v[146:147], s[6:7]
	v_cvt_pk_bf16_f32 v150, v150, v151
	v_cvt_pk_bf16_f32 v151, v152, v153
	global_store_dwordx2 v103, v[150:151], s[8:9]
	v_cvt_pk_bf16_f32 v154, v154, v155
	v_cvt_pk_bf16_f32 v155, v156, v157
	global_store_dwordx2 v103, v[154:155], s[6:7]
	s_cbranch_vccnz .LBB0_601
